# v35 + gate counted wait + single-barrier prologue transposes (bundle of wait/barrier removals)
# baseline (speedup 1.0000x reference)
; #define LAS __attribute__((address_space(3)))
; __device__ __forceinline__ void transpose_item(const float* W, int K, int N, bf16_t* WT, int item, int gu, LAS float* tile,
;                                                const float* gam = nullptr, const float* bet = nullptr, float* c1p = nullptr, float* c2p = nullptr) {
;     const int tid = threadIdx.x, nblk = N / 64, kb = item / nblk, nb = item % nblk, k0 = kb * 64, n0 = nb * 64;
;     { const int r = tid >> 3, c8 = (tid & 7) * 8; const float* src = W + (size_t)(k0 + r) * N + n0 + c8;
;       const f32x4 a = *(const GASP f32x4*)src, b = *(const GASP f32x4*)(src + 4);
;       LAS float* t = tile + r * 65 + c8; t[0] = a[0]; t[1] = a[1]; t[2] = a[2]; t[3] = a[3]; t[4] = b[0]; t[5] = b[1]; t[6] = b[2]; t[7] = b[3]; }
;     __syncthreads();
;     { const int n = tid >> 3, k8 = (tid & 7) * 8; const LAS float* t = tile + k8 * 65 + n;
;       float w[8];
; #pragma unroll
;       for (int i = 0; i < 8; ++i) w[i] = t[i * 65];
;       int nn = n0 + n; if (gu) nn = (nn < FF) ? ((nn >> 7) * 256 + (nn & 127)) : (((nn - FF) >> 7) * 256 + 128 + ((nn - FF) & 127));
;       float s2 = 0.f;
;       if (gam) {
; #pragma unroll
;           for (int i = 0; i < 8; ++i) { s2 += bet[k0 + k8 + i] * w[i]; w[i] *= gam[k0 + k8 + i]; }
;       }
;       u32x4 o; o.x = pk2(w[0], w[1]); o.y = pk2(w[2], w[3]); o.z = pk2(w[4], w[5]); o.w = pk2(w[6], w[7]);
;       *(GASP u32x4*)(WT + (size_t)nn * K + k0 + k8) = o;
;       if (gam) {
;           float s1 = ((__uint_as_float(o.x << 16) + __uint_as_float(o.x & 0xffff0000u)) + (__uint_as_float(o.y << 16) + __uint_as_float(o.y & 0xffff0000u)))
;                    + ((__uint_as_float(o.z << 16) + __uint_as_float(o.z & 0xffff0000u)) + (__uint_as_float(o.w << 16) + __uint_as_float(o.w & 0xffff0000u)));
;           s1 += __shfl_xor(s1, 1); s1 += __shfl_xor(s1, 2); s1 += __shfl_xor(s1, 4);
;           s2 += __shfl_xor(s2, 1); s2 += __shfl_xor(s2, 2); s2 += __shfl_xor(s2, 4);
;           if ((tid & 7) == 0) { c1p[(size_t)kb * NC12 + nn] = s1; c2p[(size_t)kb * NC12 + nn] = s2; }
;       } }
;     __syncthreads();
; }
; __device__ __forceinline__ void phase_prep(const Params& p, LAS unsigned char* lds) {
;     ...
;     for (int it = bx; it < NIT; it += G) {
;         int r = it;
;         if (r < I_GU) { transpose_item(p.in[7], D, 2 * FF, (bf16_t*)(ws + O_WGU1), r, 1, tile); continue; } r -= I_GU;
.LBB0_23:
	v_xor_b32_e32 v18, 0x8000, v18
	v_xor_b32_e32 v19, 0x8000, v19
	v_xor_b32_e32 v22, 0x8000, v22
	s_cmpk_gt_i32 s90, 0x57f
	s_mov_b64 s[8:9], -1
	s_cbranch_scc0 .LBB0_82
	s_cmpk_gt_u32 s90, 0xaff
	s_cbranch_scc0 .LBB0_68
	s_cmpk_gt_u32 s90, 0xdbf
	s_cbranch_scc0 .LBB0_65
	s_cmpk_gt_u32 s90, 0x107f
	s_cbranch_scc0 .LBB0_62
	s_cmpk_gt_u32 s90, 0x12ff
	s_cbranch_scc0 .LBB0_52
	s_cmpk_gt_u32 s90, 0x13ff
	s_cbranch_scc0 .LBB0_49
	s_and_b32 s91, s0, 0x3c0
	s_cmpk_gt_u32 s90, 0x14ff
	s_cbranch_scc0 .LBB0_39
	s_and_b32 s10, s5, 0x3c0
	s_cmpk_gt_u32 s90, 0x15ff
	v_add_lshl_u32 v0, s10, v5, 10
	s_cbranch_scc0 .LBB0_36
	s_cmpk_gt_u32 s90, 0x16ff
	s_cbranch_scc0 .LBB0_33
	v_lshlrev_b32_e32 v6, 2, v0
	v_lshl_add_u64 v[2:3], s[48:49], 0, v[6:7]
	s_lshl_b32 s96, s91, 2
	v_lshl_add_u64 v[2:3], v[2:3], 0, s[96:97]
	v_mov_b32_e32 v9, v7
	v_lshl_add_u64 v[2:3], v[2:3], 0, v[8:9]
	global_load_dwordx4 v[12:15], v[2:3], off nt
	global_load_dwordx4 v[24:27], v[2:3], off offset:16 nt
	v_readlane_b32 s8, v252, 8
	v_add_lshl_u32 v6, s91, v5, 11
	v_readlane_b32 s9, v252, 9
	s_lshl_b32 s96, s10, 1
	v_mov_b32_e32 v11, v7
	v_lshl_add_u64 v[2:3], s[8:9], 0, v[6:7]
	v_lshl_add_u64 v[2:3], v[2:3], 0, s[96:97]
	v_lshl_add_u64 v[2:3], v[2:3], 0, v[10:11]
	s_mov_b64 s[8:9], 0
	s_waitcnt vmcnt(0)
	ds_write2_b32 v18, v12, v13 offset1:1
	ds_write2_b32 v18, v14, v15 offset0:2 offset1:3
	ds_write2_b32 v18, v24, v25 offset0:4 offset1:5
	ds_write2_b32 v18, v26, v27 offset0:6 offset1:7
	s_waitcnt lgkmcnt(0)
	s_barrier
	ds_read2_b32 v[12:13], v19 offset1:65
	ds_read2_b32 v[14:15], v19 offset0:130 offset1:195
	ds_read2_b32 v[16:17], v22 offset0:4 offset1:69
	ds_read2_b32 v[24:25], v22 offset0:134 offset1:199
	s_waitcnt lgkmcnt(3)
	v_cvt_pk_bf16_f32 v12, v12, v13
	s_waitcnt lgkmcnt(2)
	v_cvt_pk_bf16_f32 v13, v14, v15
	s_waitcnt lgkmcnt(1)
	v_cvt_pk_bf16_f32 v14, v16, v17
	s_waitcnt lgkmcnt(0)
	v_cvt_pk_bf16_f32 v15, v24, v25
	global_store_dwordx4 v[2:3], v[12:15], off
.LBB0_33:
	s_andn2_b64 vcc, exec, s[8:9]
	s_cbranch_vccnz .LBB0_35
	v_lshlrev_b32_e32 v6, 2, v0
	v_lshl_add_u64 v[2:3], s[46:47], 0, v[6:7]
	s_lshl_b32 s96, s91, 2
	v_lshl_add_u64 v[2:3], v[2:3], 0, s[96:97]
	v_mov_b32_e32 v9, v7
	v_lshl_add_u64 v[2:3], v[2:3], 0, v[8:9]
	global_load_dwordx4 v[12:15], v[2:3], off nt
	global_load_dwordx4 v[24:27], v[2:3], off offset:16 nt
	v_readlane_b32 s8, v252, 10
	v_add_lshl_u32 v6, s91, v5, 11
	v_readlane_b32 s9, v252, 11
	s_lshl_b32 s96, s10, 1
	v_mov_b32_e32 v11, v7
	v_lshl_add_u64 v[2:3], s[8:9], 0, v[6:7]
	v_lshl_add_u64 v[2:3], v[2:3], 0, s[96:97]
	v_lshl_add_u64 v[2:3], v[2:3], 0, v[10:11]
	s_waitcnt vmcnt(0)
	ds_write2_b32 v18, v12, v13 offset1:1
	ds_write2_b32 v18, v14, v15 offset0:2 offset1:3
	ds_write2_b32 v18, v24, v25 offset0:4 offset1:5
	ds_write2_b32 v18, v26, v27 offset0:6 offset1:7
	s_waitcnt lgkmcnt(0)
	s_barrier
	ds_read2_b32 v[12:13], v19 offset1:65
	ds_read2_b32 v[14:15], v19 offset0:130 offset1:195
	ds_read2_b32 v[16:17], v22 offset0:4 offset1:69
	ds_read2_b32 v[24:25], v22 offset0:134 offset1:199
	s_waitcnt lgkmcnt(3)
	v_cvt_pk_bf16_f32 v12, v12, v13
	s_waitcnt lgkmcnt(2)
	v_cvt_pk_bf16_f32 v13, v14, v15
	s_waitcnt lgkmcnt(1)
	v_cvt_pk_bf16_f32 v14, v16, v17
	s_waitcnt lgkmcnt(0)
	v_cvt_pk_bf16_f32 v15, v24, v25
	global_store_dwordx4 v[2:3], v[12:15], off
.LBB0_35:
	s_mov_b64 s[8:9], 0
.LBB0_36:
	s_andn2_b64 vcc, exec, s[8:9]
	s_cbranch_vccnz .LBB0_38
	v_lshlrev_b32_e32 v6, 2, v0
	v_lshl_add_u64 v[0:1], s[44:45], 0, v[6:7]
	s_lshl_b32 s96, s91, 2
	v_lshl_add_u64 v[0:1], v[0:1], 0, s[96:97]
	v_mov_b32_e32 v9, v7
	v_lshl_add_u64 v[12:13], v[0:1], 0, v[8:9]
	global_load_dwordx4 v[0:3], v[12:13], off nt
	s_nop 0
	global_load_dwordx4 v[12:15], v[12:13], off offset:16 nt
	v_add_lshl_u32 v6, s91, v5, 11
	v_lshl_add_u64 v[16:17], s[62:63], 0, v[6:7]
	s_lshl_b32 s96, s10, 1
	v_mov_b32_e32 v11, v7
	v_lshl_add_u64 v[16:17], v[16:17], 0, s[96:97]
	v_lshl_add_u64 v[16:17], v[16:17], 0, v[10:11]
	s_waitcnt vmcnt(0)
	ds_write2_b32 v18, v0, v1 offset1:1
	ds_write2_b32 v18, v2, v3 offset0:2 offset1:3
	ds_write2_b32 v18, v12, v13 offset0:4 offset1:5
	ds_write2_b32 v18, v14, v15 offset0:6 offset1:7
	s_waitcnt lgkmcnt(0)
	s_barrier
	ds_read2_b32 v[0:1], v19 offset1:65
	ds_read2_b32 v[2:3], v19 offset0:130 offset1:195
	ds_read2_b32 v[12:13], v22 offset0:4 offset1:69
	ds_read2_b32 v[14:15], v22 offset0:134 offset1:199
	s_waitcnt lgkmcnt(3)
	v_cvt_pk_bf16_f32 v0, v0, v1
	s_waitcnt lgkmcnt(2)
	v_cvt_pk_bf16_f32 v1, v2, v3
	s_waitcnt lgkmcnt(1)
	v_cvt_pk_bf16_f32 v2, v12, v13
	s_waitcnt lgkmcnt(0)
	v_cvt_pk_bf16_f32 v3, v14, v15
	global_store_dwordx4 v[16:17], v[0:3], off
.LBB0_38:
	s_mov_b64 s[8:9], 0

; #define LAS __attribute__((address_space(3)))
; #define GASP __attribute__((address_space(1)))
; __device__ __forceinline__ void transpose_item(const float* W, int K, int N, bf16_t* WT, int item, int gu, LAS float* tile,
;                                                const float* gam = nullptr, const float* bet = nullptr, float* c1p = nullptr, float* c2p = nullptr) {
;     const int tid = threadIdx.x, nblk = N / 64, kb = item / nblk, nb = item % nblk, k0 = kb * 64, n0 = nb * 64;
;     { const int r = tid >> 3, c8 = (tid & 7) * 8; const float* src = W + (size_t)(k0 + r) * N + n0 + c8;
;       const f32x4 a = *(const GASP f32x4*)src, b = *(const GASP f32x4*)(src + 4);
;       LAS float* t = tile + r * 65 + c8; t[0] = a[0]; t[1] = a[1]; t[2] = a[2]; t[3] = a[3]; t[4] = b[0]; t[5] = b[1]; t[6] = b[2]; t[7] = b[3]; }
;     __syncthreads();
;     { const int n = tid >> 3, k8 = (tid & 7) * 8; const LAS float* t = tile + k8 * 65 + n;
;       float w[8];
; #pragma unroll
;       for (int i = 0; i < 8; ++i) w[i] = t[i * 65];
;       int nn = n0 + n; if (gu) nn = (nn < FF) ? ((nn >> 7) * 256 + (nn & 127)) : (((nn - FF) >> 7) * 256 + 128 + ((nn - FF) & 127));
;       float s2 = 0.f;
;       if (gam) {
; #pragma unroll
;           for (int i = 0; i < 8; ++i) { s2 += bet[k0 + k8 + i] * w[i]; w[i] *= gam[k0 + k8 + i]; }
;       }
;       u32x4 o; o.x = pk2(w[0], w[1]); o.y = pk2(w[2], w[3]); o.z = pk2(w[4], w[5]); o.w = pk2(w[6], w[7]);
;       *(GASP u32x4*)(WT + (size_t)nn * K + k0 + k8) = o;
;       if (gam) {
;           float s1 = ((__uint_as_float(o.x << 16) + __uint_as_float(o.x & 0xffff0000u)) + (__uint_as_float(o.y << 16) + __uint_as_float(o.y & 0xffff0000u)))
;                    + ((__uint_as_float(o.z << 16) + __uint_as_float(o.z & 0xffff0000u)) + (__uint_as_float(o.w << 16) + __uint_as_float(o.w & 0xffff0000u)));
;           s1 += __shfl_xor(s1, 1); s1 += __shfl_xor(s1, 2); s1 += __shfl_xor(s1, 4);
;           s2 += __shfl_xor(s2, 1); s2 += __shfl_xor(s2, 2); s2 += __shfl_xor(s2, 4);
;           if ((tid & 7) == 0) { c1p[(size_t)kb * NC12 + nn] = s1; c2p[(size_t)kb * NC12 + nn] = s2; }
;       } }
;     __syncthreads();
; }
; __device__ __forceinline__ void phase_prep(const Params& p, LAS unsigned char* lds) {
;     ...
;         if (r < I_SQ) { transpose_item(p.in[21], D, D, (bf16_t*)(ws + O_WOUT), r, 0, tile); continue; } r -= I_SQ;
.LBB0_49:
	s_andn2_b64 vcc, exec, s[8:9]
	s_cbranch_vccnz .LBB0_51
	s_and_b32 s8, s5, 0x3c0
	s_and_b32 s9, s0, 0x3c0
	v_add_lshl_u32 v6, s8, v5, 12
	v_lshl_add_u64 v[0:1], s[36:37], 0, v[6:7]
	s_lshl_b32 s96, s9, 2
	v_lshl_add_u64 v[0:1], v[0:1], 0, s[96:97]
	v_mov_b32_e32 v9, v7
	v_lshl_add_u64 v[12:13], v[0:1], 0, v[8:9]
	global_load_dwordx4 v[0:3], v[12:13], off nt
	s_nop 0
	global_load_dwordx4 v[12:15], v[12:13], off offset:16 nt
	v_add_lshl_u32 v6, s9, v5, 11
	v_lshl_add_u64 v[16:17], s[70:71], 0, v[6:7]
	s_lshl_b32 s96, s8, 1
	v_mov_b32_e32 v11, v7
	v_lshl_add_u64 v[16:17], v[16:17], 0, s[96:97]
	v_lshl_add_u64 v[16:17], v[16:17], 0, v[10:11]
	s_waitcnt vmcnt(0)
	ds_write2_b32 v18, v0, v1 offset1:1
	ds_write2_b32 v18, v2, v3 offset0:2 offset1:3
	ds_write2_b32 v18, v12, v13 offset0:4 offset1:5
	ds_write2_b32 v18, v14, v15 offset0:6 offset1:7
	s_waitcnt lgkmcnt(0)
	s_barrier
	ds_read2_b32 v[0:1], v19 offset1:65
	ds_read2_b32 v[2:3], v19 offset0:130 offset1:195
	ds_read2_b32 v[12:13], v22 offset0:4 offset1:69
	ds_read2_b32 v[14:15], v22 offset0:134 offset1:199
	s_waitcnt lgkmcnt(3)
	v_cvt_pk_bf16_f32 v0, v0, v1
	s_waitcnt lgkmcnt(2)
	v_cvt_pk_bf16_f32 v1, v2, v3
	s_waitcnt lgkmcnt(1)
	v_cvt_pk_bf16_f32 v2, v12, v13
	s_waitcnt lgkmcnt(0)
	v_cvt_pk_bf16_f32 v3, v14, v15
	global_store_dwordx4 v[16:17], v[0:3], off
.LBB0_51:
	s_mov_b64 s[8:9], 0

; __device__ __forceinline__ void transpose_item(const float* W, int K, int N, bf16_t* WT, int item, int gu, LAS float* tile,
;                                                const float* gam = nullptr, const float* bet = nullptr, float* c1p = nullptr, float* c2p = nullptr) {
;     const int tid = threadIdx.x, nblk = N / 64, kb = item / nblk, nb = item % nblk, k0 = kb * 64, n0 = nb * 64;
;     { const int r = tid >> 3, c8 = (tid & 7) * 8; const float* src = W + (size_t)(k0 + r) * N + n0 + c8;
;       const f32x4 a = *(const GASP f32x4*)src, b = *(const GASP f32x4*)(src + 4);
;       LAS float* t = tile + r * 65 + c8; t[0] = a[0]; t[1] = a[1]; t[2] = a[2]; t[3] = a[3]; t[4] = b[0]; t[5] = b[1]; t[6] = b[2]; t[7] = b[3]; }
;     __syncthreads();
;     { const int n = tid >> 3, k8 = (tid & 7) * 8; const LAS float* t = tile + k8 * 65 + n;
;       float w[8];
; #pragma unroll
;       for (int i = 0; i < 8; ++i) w[i] = t[i * 65];
;       int nn = n0 + n; if (gu) nn = (nn < FF) ? ((nn >> 7) * 256 + (nn & 127)) : (((nn - FF) >> 7) * 256 + 128 + ((nn - FF) & 127));
;       float s2 = 0.f;
;       if (gam) {
; #pragma unroll
;           for (int i = 0; i < 8; ++i) { s2 += bet[k0 + k8 + i] * w[i]; w[i] *= gam[k0 + k8 + i]; }
;       }
;       u32x4 o; o.x = pk2(w[0], w[1]); o.y = pk2(w[2], w[3]); o.z = pk2(w[4], w[5]); o.w = pk2(w[6], w[7]);
;       *(GASP u32x4*)(WT + (size_t)nn * K + k0 + k8) = o;
;       if (gam) {
;           float s1 = ((__uint_as_float(o.x << 16) + __uint_as_float(o.x & 0xffff0000u)) + (__uint_as_float(o.y << 16) + __uint_as_float(o.y & 0xffff0000u)))
;                    + ((__uint_as_float(o.z << 16) + __uint_as_float(o.z & 0xffff0000u)) + (__uint_as_float(o.w << 16) + __uint_as_float(o.w & 0xffff0000u)));
;           s1 += __shfl_xor(s1, 1); s1 += __shfl_xor(s1, 2); s1 += __shfl_xor(s1, 4);
;           s2 += __shfl_xor(s2, 1); s2 += __shfl_xor(s2, 2); s2 += __shfl_xor(s2, 4);
;           if ((tid & 7) == 0) { c1p[(size_t)kb * NC12 + nn] = s1; c2p[(size_t)kb * NC12 + nn] = s2; }
;       } }
;     __syncthreads();
; }
; __device__ __forceinline__ void phase_prep(const Params& p, LAS unsigned char* lds) {
;     ...
;         if (r < I_DN) { transpose_item(p.in[8], FF, D, (bf16_t*)(ws + O_WDN1), r, 0, tile); continue; } r -= I_DN;
;         if (r < I_DN) { transpose_item(p.in[31], FF, D, (bf16_t*)(ws + O_WDN2), r, 0, tile); continue; } r -= I_DN;
.LBB0_62:
	s_andn2_b64 vcc, exec, s[8:9]
	s_cbranch_vccnz .LBB0_64
	s_add_i32 s8, s5, 0x3c900
	s_and_b32 s10, s8, 0x3ffc0
	v_readlane_b32 s8, v252, 1
	v_readlane_b32 s9, v252, 2
	s_load_dwordx2 s[8:9], s[8:9], 0xf8
	s_and_b32 s11, s0, 0x3c0
	v_add_lshl_u32 v6, s10, v5, 12
	s_lshl_b32 s96, s11, 2
	v_mov_b32_e32 v9, v7
	s_waitcnt lgkmcnt(0)
	v_lshl_add_u64 v[0:1], s[8:9], 0, v[6:7]
	v_lshl_add_u64 v[0:1], v[0:1], 0, s[96:97]
	v_lshl_add_u64 v[12:13], v[0:1], 0, v[8:9]
	global_load_dwordx4 v[0:3], v[12:13], off nt
	s_nop 0
	global_load_dwordx4 v[12:15], v[12:13], off offset:16 nt
	v_add_u32_e32 v6, s11, v5
	v_mul_u32_u24_e32 v6, 0xb00, v6
	v_lshlrev_b32_e32 v6, 1, v6
	v_lshl_add_u64 v[16:17], s[78:79], 0, v[6:7]
	s_lshl_b32 s96, s10, 1
	v_mov_b32_e32 v11, v7
	v_lshl_add_u64 v[16:17], v[16:17], 0, s[96:97]
	v_lshl_add_u64 v[16:17], v[16:17], 0, v[10:11]
	s_waitcnt vmcnt(0)
	ds_write2_b32 v18, v0, v1 offset1:1
	ds_write2_b32 v18, v2, v3 offset0:2 offset1:3
	ds_write2_b32 v18, v12, v13 offset0:4 offset1:5
	ds_write2_b32 v18, v14, v15 offset0:6 offset1:7
	s_waitcnt lgkmcnt(0)
	s_barrier
	ds_read2_b32 v[0:1], v19 offset1:65
	ds_read2_b32 v[2:3], v19 offset0:130 offset1:195
	ds_read2_b32 v[12:13], v22 offset0:4 offset1:69
	ds_read2_b32 v[14:15], v22 offset0:134 offset1:199
	s_waitcnt lgkmcnt(3)
	v_cvt_pk_bf16_f32 v0, v0, v1
	s_waitcnt lgkmcnt(2)
	v_cvt_pk_bf16_f32 v1, v2, v3
	s_waitcnt lgkmcnt(1)
	v_cvt_pk_bf16_f32 v2, v12, v13
	s_waitcnt lgkmcnt(0)
	v_cvt_pk_bf16_f32 v3, v14, v15
	global_store_dwordx4 v[16:17], v[0:3], off
.LBB0_64:
	s_mov_b64 s[8:9], 0
.LBB0_65:
	s_andn2_b64 vcc, exec, s[8:9]
	s_cbranch_vccnz .LBB0_67
	s_add_i32 s8, s5, 0x3d400
	s_and_b32 s8, s8, 0x3ffc0
	s_and_b32 s9, s0, 0x3c0
	v_add_lshl_u32 v6, s8, v5, 12
	v_lshl_add_u64 v[0:1], s[20:21], 0, v[6:7]
	s_lshl_b32 s96, s9, 2
	v_lshl_add_u64 v[0:1], v[0:1], 0, s[96:97]
	v_mov_b32_e32 v9, v7
	v_lshl_add_u64 v[12:13], v[0:1], 0, v[8:9]
	global_load_dwordx4 v[0:3], v[12:13], off nt
	s_nop 0
	global_load_dwordx4 v[12:15], v[12:13], off offset:16 nt
	v_add_u32_e32 v6, s9, v5
	v_mul_u32_u24_e32 v6, 0xb00, v6
	v_lshlrev_b32_e32 v6, 1, v6
	v_lshl_add_u64 v[16:17], s[80:81], 0, v[6:7]
	s_lshl_b32 s96, s8, 1
	v_mov_b32_e32 v11, v7
	v_lshl_add_u64 v[16:17], v[16:17], 0, s[96:97]
	v_lshl_add_u64 v[16:17], v[16:17], 0, v[10:11]
	s_waitcnt vmcnt(0)
	ds_write2_b32 v18, v0, v1 offset1:1
	ds_write2_b32 v18, v2, v3 offset0:2 offset1:3
	ds_write2_b32 v18, v12, v13 offset0:4 offset1:5
	ds_write2_b32 v18, v14, v15 offset0:6 offset1:7
	s_waitcnt lgkmcnt(0)
	s_barrier
	ds_read2_b32 v[0:1], v19 offset1:65
	ds_read2_b32 v[2:3], v19 offset0:130 offset1:195
	ds_read2_b32 v[12:13], v22 offset0:4 offset1:69
	ds_read2_b32 v[14:15], v22 offset0:134 offset1:199
	s_waitcnt lgkmcnt(3)
	v_cvt_pk_bf16_f32 v0, v0, v1
	s_waitcnt lgkmcnt(2)
	v_cvt_pk_bf16_f32 v1, v2, v3
	s_waitcnt lgkmcnt(1)
	v_cvt_pk_bf16_f32 v2, v12, v13
	s_waitcnt lgkmcnt(0)
	v_cvt_pk_bf16_f32 v3, v14, v15
	global_store_dwordx4 v[16:17], v[0:3], off
.LBB0_67:
	s_mov_b64 s[8:9], 0
